# EpiUp epilogue rewritten (straight-line, SGPR-base addressing, 42 ops per row block) on top of EpiIn/EpiRes/P0/final-norm rewrites
# speedup vs baseline: 1.0516x; 1.0028x over previous
.LBB0_798:
	s_mov_b64 s[20:21], -1
	v_lshlrev_b32_e32 v138, 13, v140
	v_lshl_add_u32 v138, v142, 1, v138
	s_lshl_b32 s10, s40, 21
	s_lshl_b32 s11, s41, 9
	s_add_i32 s10, s10, s11
	s_add_u32 s100, s88, s10
	s_addc_u32 s101, s89, 0
	s_waitcnt vmcnt(0)
	v_fmamk_f32 v160, v160, 0x3a800000, v228
	v_fmamk_f32 v161, v161, 0x3a800000, v228
	v_fmamk_f32 v162, v162, 0x3a800000, v228
	v_fmamk_f32 v163, v163, 0x3a800000, v228
	v_fmamk_f32 v164, v164, 0x3a800000, v228
	v_fmamk_f32 v165, v165, 0x3a800000, v228
	v_fmamk_f32 v166, v166, 0x3a800000, v228
	v_fmamk_f32 v167, v167, 0x3a800000, v228
	v_rsq_f32_e32 v160, v160
	v_rsq_f32_e32 v161, v161
	v_rsq_f32_e32 v162, v162
	v_rsq_f32_e32 v163, v163
	v_rsq_f32_e32 v164, v164
	v_rsq_f32_e32 v165, v165
	v_rsq_f32_e32 v166, v166
	v_rsq_f32_e32 v167, v167
	v_pk_mul_f32 v[124:125], v[124:125], v[160:161] op_sel_hi:[1,0]
	v_pk_mul_f32 v[126:127], v[126:127], v[160:161] op_sel_hi:[1,0]
	v_pk_mul_f32 v[120:121], v[120:121], v[160:161] op_sel_hi:[1,0]
	v_pk_mul_f32 v[122:123], v[122:123], v[160:161] op_sel_hi:[1,0]
	v_pk_mul_f32 v[116:117], v[116:117], v[160:161] op_sel_hi:[1,0]
	v_pk_mul_f32 v[118:119], v[118:119], v[160:161] op_sel_hi:[1,0]
	v_pk_mul_f32 v[112:113], v[112:113], v[160:161] op_sel_hi:[1,0]
	v_pk_mul_f32 v[114:115], v[114:115], v[160:161] op_sel_hi:[1,0]
	v_max_f32_e32 v124, 0, v124
	v_max_f32_e32 v125, 0, v125
	v_max_f32_e32 v126, 0, v126
	v_max_f32_e32 v127, 0, v127
	v_max_f32_e32 v120, 0, v120
	v_max_f32_e32 v121, 0, v121
	v_max_f32_e32 v122, 0, v122
	v_max_f32_e32 v123, 0, v123
	v_max_f32_e32 v116, 0, v116
	v_max_f32_e32 v117, 0, v117
	v_max_f32_e32 v118, 0, v118
	v_max_f32_e32 v119, 0, v119
	v_max_f32_e32 v112, 0, v112
	v_max_f32_e32 v113, 0, v113
	v_max_f32_e32 v114, 0, v114
	v_max_f32_e32 v115, 0, v115
	v_pk_mul_f32 v[124:125], v[124:125], v[124:125]
	v_pk_mul_f32 v[126:127], v[126:127], v[126:127]
	v_pk_mul_f32 v[120:121], v[120:121], v[120:121]
	v_pk_mul_f32 v[122:123], v[122:123], v[122:123]
	v_pk_mul_f32 v[116:117], v[116:117], v[116:117]
	v_pk_mul_f32 v[118:119], v[118:119], v[118:119]
	v_pk_mul_f32 v[112:113], v[112:113], v[112:113]
	v_pk_mul_f32 v[114:115], v[114:115], v[114:115]
	v_cvt_pk_bf16_f32 v124, v124, v125
	v_cvt_pk_bf16_f32 v125, v126, v127
	v_cvt_pk_bf16_f32 v126, v120, v121
	v_cvt_pk_bf16_f32 v127, v122, v123
	global_store_dwordx4 v138, v[124:127], s[100:101]
	v_cvt_pk_bf16_f32 v116, v116, v117
	v_cvt_pk_bf16_f32 v117, v118, v119
	v_cvt_pk_bf16_f32 v118, v112, v113
	v_cvt_pk_bf16_f32 v119, v114, v115
	global_store_dwordx4 v138, v[116:119], s[100:101] offset:256
	s_add_u32 s100, s100, 0x20000
	s_addc_u32 s101, s101, 0
	v_pk_mul_f32 v[108:109], v[108:109], v[160:161] op_sel:[0,1] op_sel_hi:[1,1]
	v_pk_mul_f32 v[110:111], v[110:111], v[160:161] op_sel:[0,1] op_sel_hi:[1,1]
	v_pk_mul_f32 v[104:105], v[104:105], v[160:161] op_sel:[0,1] op_sel_hi:[1,1]
	v_pk_mul_f32 v[106:107], v[106:107], v[160:161] op_sel:[0,1] op_sel_hi:[1,1]
	v_pk_mul_f32 v[100:101], v[100:101], v[160:161] op_sel:[0,1] op_sel_hi:[1,1]
	v_pk_mul_f32 v[102:103], v[102:103], v[160:161] op_sel:[0,1] op_sel_hi:[1,1]
	v_pk_mul_f32 v[96:97], v[96:97], v[160:161] op_sel:[0,1] op_sel_hi:[1,1]
	v_pk_mul_f32 v[98:99], v[98:99], v[160:161] op_sel:[0,1] op_sel_hi:[1,1]
	v_max_f32_e32 v108, 0, v108
	v_max_f32_e32 v109, 0, v109
	v_max_f32_e32 v110, 0, v110
	v_max_f32_e32 v111, 0, v111
	v_max_f32_e32 v104, 0, v104
	v_max_f32_e32 v105, 0, v105
	v_max_f32_e32 v106, 0, v106
	v_max_f32_e32 v107, 0, v107
	v_max_f32_e32 v100, 0, v100
	v_max_f32_e32 v101, 0, v101
	v_max_f32_e32 v102, 0, v102
	v_max_f32_e32 v103, 0, v103
	v_max_f32_e32 v96, 0, v96
	v_max_f32_e32 v97, 0, v97
	v_max_f32_e32 v98, 0, v98
	v_max_f32_e32 v99, 0, v99
	v_pk_mul_f32 v[108:109], v[108:109], v[108:109]
	v_pk_mul_f32 v[110:111], v[110:111], v[110:111]
	v_pk_mul_f32 v[104:105], v[104:105], v[104:105]
	v_pk_mul_f32 v[106:107], v[106:107], v[106:107]
	v_pk_mul_f32 v[100:101], v[100:101], v[100:101]
	v_pk_mul_f32 v[102:103], v[102:103], v[102:103]
	v_pk_mul_f32 v[96:97], v[96:97], v[96:97]
	v_pk_mul_f32 v[98:99], v[98:99], v[98:99]
	v_cvt_pk_bf16_f32 v108, v108, v109
	v_cvt_pk_bf16_f32 v109, v110, v111
	v_cvt_pk_bf16_f32 v110, v104, v105
	v_cvt_pk_bf16_f32 v111, v106, v107
	global_store_dwordx4 v138, v[108:111], s[100:101]
	v_cvt_pk_bf16_f32 v100, v100, v101
	v_cvt_pk_bf16_f32 v101, v102, v103
	v_cvt_pk_bf16_f32 v102, v96, v97
	v_cvt_pk_bf16_f32 v103, v98, v99
	global_store_dwordx4 v138, v[100:103], s[100:101] offset:256
	s_add_u32 s100, s100, 0x20000
	s_addc_u32 s101, s101, 0
	v_pk_mul_f32 v[92:93], v[92:93], v[162:163] op_sel_hi:[1,0]
	v_pk_mul_f32 v[94:95], v[94:95], v[162:163] op_sel_hi:[1,0]
	v_pk_mul_f32 v[88:89], v[88:89], v[162:163] op_sel_hi:[1,0]
	v_pk_mul_f32 v[90:91], v[90:91], v[162:163] op_sel_hi:[1,0]
	v_pk_mul_f32 v[84:85], v[84:85], v[162:163] op_sel_hi:[1,0]
	v_pk_mul_f32 v[86:87], v[86:87], v[162:163] op_sel_hi:[1,0]
	v_pk_mul_f32 v[80:81], v[80:81], v[162:163] op_sel_hi:[1,0]
	v_pk_mul_f32 v[82:83], v[82:83], v[162:163] op_sel_hi:[1,0]
	v_max_f32_e32 v92, 0, v92
	v_max_f32_e32 v93, 0, v93
	v_max_f32_e32 v94, 0, v94
	v_max_f32_e32 v95, 0, v95
	v_max_f32_e32 v88, 0, v88
	v_max_f32_e32 v89, 0, v89
	v_max_f32_e32 v90, 0, v90
	v_max_f32_e32 v91, 0, v91
	v_max_f32_e32 v84, 0, v84
	v_max_f32_e32 v85, 0, v85
	v_max_f32_e32 v86, 0, v86
	v_max_f32_e32 v87, 0, v87
	v_max_f32_e32 v80, 0, v80
	v_max_f32_e32 v81, 0, v81
	v_max_f32_e32 v82, 0, v82
	v_max_f32_e32 v83, 0, v83
	v_pk_mul_f32 v[92:93], v[92:93], v[92:93]
	v_pk_mul_f32 v[94:95], v[94:95], v[94:95]
	v_pk_mul_f32 v[88:89], v[88:89], v[88:89]
	v_pk_mul_f32 v[90:91], v[90:91], v[90:91]
	v_pk_mul_f32 v[84:85], v[84:85], v[84:85]
	v_pk_mul_f32 v[86:87], v[86:87], v[86:87]
	v_pk_mul_f32 v[80:81], v[80:81], v[80:81]
	v_pk_mul_f32 v[82:83], v[82:83], v[82:83]
	v_cvt_pk_bf16_f32 v92, v92, v93
	v_cvt_pk_bf16_f32 v93, v94, v95
	v_cvt_pk_bf16_f32 v94, v88, v89
	v_cvt_pk_bf16_f32 v95, v90, v91
	global_store_dwordx4 v138, v[92:95], s[100:101]
	v_cvt_pk_bf16_f32 v84, v84, v85
	v_cvt_pk_bf16_f32 v85, v86, v87
	v_cvt_pk_bf16_f32 v86, v80, v81
	v_cvt_pk_bf16_f32 v87, v82, v83
	global_store_dwordx4 v138, v[84:87], s[100:101] offset:256
	s_add_u32 s100, s100, 0x20000
	s_addc_u32 s101, s101, 0
	v_pk_mul_f32 v[76:77], v[76:77], v[162:163] op_sel:[0,1] op_sel_hi:[1,1]
	v_pk_mul_f32 v[78:79], v[78:79], v[162:163] op_sel:[0,1] op_sel_hi:[1,1]
	v_pk_mul_f32 v[72:73], v[72:73], v[162:163] op_sel:[0,1] op_sel_hi:[1,1]
	v_pk_mul_f32 v[74:75], v[74:75], v[162:163] op_sel:[0,1] op_sel_hi:[1,1]
	v_pk_mul_f32 v[68:69], v[68:69], v[162:163] op_sel:[0,1] op_sel_hi:[1,1]
	v_pk_mul_f32 v[70:71], v[70:71], v[162:163] op_sel:[0,1] op_sel_hi:[1,1]
	v_pk_mul_f32 v[64:65], v[64:65], v[162:163] op_sel:[0,1] op_sel_hi:[1,1]
	v_pk_mul_f32 v[66:67], v[66:67], v[162:163] op_sel:[0,1] op_sel_hi:[1,1]
	v_max_f32_e32 v76, 0, v76
	v_max_f32_e32 v77, 0, v77
	v_max_f32_e32 v78, 0, v78
	v_max_f32_e32 v79, 0, v79
	v_max_f32_e32 v72, 0, v72
	v_max_f32_e32 v73, 0, v73
	v_max_f32_e32 v74, 0, v74
	v_max_f32_e32 v75, 0, v75
	v_max_f32_e32 v68, 0, v68
	v_max_f32_e32 v69, 0, v69
	v_max_f32_e32 v70, 0, v70
	v_max_f32_e32 v71, 0, v71
	v_max_f32_e32 v64, 0, v64
	v_max_f32_e32 v65, 0, v65
	v_max_f32_e32 v66, 0, v66
	v_max_f32_e32 v67, 0, v67
	v_pk_mul_f32 v[76:77], v[76:77], v[76:77]
	v_pk_mul_f32 v[78:79], v[78:79], v[78:79]
	v_pk_mul_f32 v[72:73], v[72:73], v[72:73]
	v_pk_mul_f32 v[74:75], v[74:75], v[74:75]
	v_pk_mul_f32 v[68:69], v[68:69], v[68:69]
	v_pk_mul_f32 v[70:71], v[70:71], v[70:71]
	v_pk_mul_f32 v[64:65], v[64:65], v[64:65]
	v_pk_mul_f32 v[66:67], v[66:67], v[66:67]
	v_cvt_pk_bf16_f32 v76, v76, v77
	v_cvt_pk_bf16_f32 v77, v78, v79
	v_cvt_pk_bf16_f32 v78, v72, v73
	v_cvt_pk_bf16_f32 v79, v74, v75
	global_store_dwordx4 v138, v[76:79], s[100:101]
	v_cvt_pk_bf16_f32 v68, v68, v69
	v_cvt_pk_bf16_f32 v69, v70, v71
	v_cvt_pk_bf16_f32 v70, v64, v65
	v_cvt_pk_bf16_f32 v71, v66, v67
	global_store_dwordx4 v138, v[68:71], s[100:101] offset:256
	s_add_u32 s100, s100, 0xa0000
	s_addc_u32 s101, s101, 0
	v_pk_mul_f32 v[60:61], v[60:61], v[164:165] op_sel_hi:[1,0]
	v_pk_mul_f32 v[62:63], v[62:63], v[164:165] op_sel_hi:[1,0]
	v_pk_mul_f32 v[56:57], v[56:57], v[164:165] op_sel_hi:[1,0]
	v_pk_mul_f32 v[58:59], v[58:59], v[164:165] op_sel_hi:[1,0]
	v_pk_mul_f32 v[52:53], v[52:53], v[164:165] op_sel_hi:[1,0]
	v_pk_mul_f32 v[54:55], v[54:55], v[164:165] op_sel_hi:[1,0]
	v_pk_mul_f32 v[48:49], v[48:49], v[164:165] op_sel_hi:[1,0]
	v_pk_mul_f32 v[50:51], v[50:51], v[164:165] op_sel_hi:[1,0]
	v_max_f32_e32 v60, 0, v60
	v_max_f32_e32 v61, 0, v61
	v_max_f32_e32 v62, 0, v62
	v_max_f32_e32 v63, 0, v63
	v_max_f32_e32 v56, 0, v56
	v_max_f32_e32 v57, 0, v57
	v_max_f32_e32 v58, 0, v58
	v_max_f32_e32 v59, 0, v59
	v_max_f32_e32 v52, 0, v52
	v_max_f32_e32 v53, 0, v53
	v_max_f32_e32 v54, 0, v54
	v_max_f32_e32 v55, 0, v55
	v_max_f32_e32 v48, 0, v48
	v_max_f32_e32 v49, 0, v49
	v_max_f32_e32 v50, 0, v50
	v_max_f32_e32 v51, 0, v51
	v_pk_mul_f32 v[60:61], v[60:61], v[60:61]
	v_pk_mul_f32 v[62:63], v[62:63], v[62:63]
	v_pk_mul_f32 v[56:57], v[56:57], v[56:57]
	v_pk_mul_f32 v[58:59], v[58:59], v[58:59]
	v_pk_mul_f32 v[52:53], v[52:53], v[52:53]
	v_pk_mul_f32 v[54:55], v[54:55], v[54:55]
	v_pk_mul_f32 v[48:49], v[48:49], v[48:49]
	v_pk_mul_f32 v[50:51], v[50:51], v[50:51]
	v_cvt_pk_bf16_f32 v60, v60, v61
	v_cvt_pk_bf16_f32 v61, v62, v63
	v_cvt_pk_bf16_f32 v62, v56, v57
	v_cvt_pk_bf16_f32 v63, v58, v59
	global_store_dwordx4 v138, v[60:63], s[100:101]
	v_cvt_pk_bf16_f32 v52, v52, v53
	v_cvt_pk_bf16_f32 v53, v54, v55
	v_cvt_pk_bf16_f32 v54, v48, v49
	v_cvt_pk_bf16_f32 v55, v50, v51
	global_store_dwordx4 v138, v[52:55], s[100:101] offset:256
	s_add_u32 s100, s100, 0x20000
	s_addc_u32 s101, s101, 0
	v_pk_mul_f32 v[44:45], v[44:45], v[164:165] op_sel:[0,1] op_sel_hi:[1,1]
	v_pk_mul_f32 v[46:47], v[46:47], v[164:165] op_sel:[0,1] op_sel_hi:[1,1]
	v_pk_mul_f32 v[40:41], v[40:41], v[164:165] op_sel:[0,1] op_sel_hi:[1,1]
	v_pk_mul_f32 v[42:43], v[42:43], v[164:165] op_sel:[0,1] op_sel_hi:[1,1]
	v_pk_mul_f32 v[36:37], v[36:37], v[164:165] op_sel:[0,1] op_sel_hi:[1,1]
	v_pk_mul_f32 v[38:39], v[38:39], v[164:165] op_sel:[0,1] op_sel_hi:[1,1]
	v_pk_mul_f32 v[32:33], v[32:33], v[164:165] op_sel:[0,1] op_sel_hi:[1,1]
	v_pk_mul_f32 v[34:35], v[34:35], v[164:165] op_sel:[0,1] op_sel_hi:[1,1]
	v_max_f32_e32 v44, 0, v44
	v_max_f32_e32 v45, 0, v45
	v_max_f32_e32 v46, 0, v46
	v_max_f32_e32 v47, 0, v47
	v_max_f32_e32 v40, 0, v40
	v_max_f32_e32 v41, 0, v41
	v_max_f32_e32 v42, 0, v42
	v_max_f32_e32 v43, 0, v43
	v_max_f32_e32 v36, 0, v36
	v_max_f32_e32 v37, 0, v37
	v_max_f32_e32 v38, 0, v38
	v_max_f32_e32 v39, 0, v39
	v_max_f32_e32 v32, 0, v32
	v_max_f32_e32 v33, 0, v33
	v_max_f32_e32 v34, 0, v34
	v_max_f32_e32 v35, 0, v35
	v_pk_mul_f32 v[44:45], v[44:45], v[44:45]
	v_pk_mul_f32 v[46:47], v[46:47], v[46:47]
	v_pk_mul_f32 v[40:41], v[40:41], v[40:41]
	v_pk_mul_f32 v[42:43], v[42:43], v[42:43]
	v_pk_mul_f32 v[36:37], v[36:37], v[36:37]
	v_pk_mul_f32 v[38:39], v[38:39], v[38:39]
	v_pk_mul_f32 v[32:33], v[32:33], v[32:33]
	v_pk_mul_f32 v[34:35], v[34:35], v[34:35]
	v_cvt_pk_bf16_f32 v44, v44, v45
	v_cvt_pk_bf16_f32 v45, v46, v47
	v_cvt_pk_bf16_f32 v46, v40, v41
	v_cvt_pk_bf16_f32 v47, v42, v43
	global_store_dwordx4 v138, v[44:47], s[100:101]
	v_cvt_pk_bf16_f32 v36, v36, v37
	v_cvt_pk_bf16_f32 v37, v38, v39
	v_cvt_pk_bf16_f32 v38, v32, v33
	v_cvt_pk_bf16_f32 v39, v34, v35
	global_store_dwordx4 v138, v[36:39], s[100:101] offset:256
	s_add_u32 s100, s100, 0x20000
	s_addc_u32 s101, s101, 0
	v_pk_mul_f32 v[28:29], v[28:29], v[166:167] op_sel_hi:[1,0]
	v_pk_mul_f32 v[30:31], v[30:31], v[166:167] op_sel_hi:[1,0]
	v_pk_mul_f32 v[24:25], v[24:25], v[166:167] op_sel_hi:[1,0]
	v_pk_mul_f32 v[26:27], v[26:27], v[166:167] op_sel_hi:[1,0]
	v_pk_mul_f32 v[20:21], v[20:21], v[166:167] op_sel_hi:[1,0]
	v_pk_mul_f32 v[22:23], v[22:23], v[166:167] op_sel_hi:[1,0]
	v_pk_mul_f32 v[16:17], v[16:17], v[166:167] op_sel_hi:[1,0]
	v_pk_mul_f32 v[18:19], v[18:19], v[166:167] op_sel_hi:[1,0]
	v_max_f32_e32 v28, 0, v28
	v_max_f32_e32 v29, 0, v29
	v_max_f32_e32 v30, 0, v30
	v_max_f32_e32 v31, 0, v31
	v_max_f32_e32 v24, 0, v24
	v_max_f32_e32 v25, 0, v25
	v_max_f32_e32 v26, 0, v26
	v_max_f32_e32 v27, 0, v27
	v_max_f32_e32 v20, 0, v20
	v_max_f32_e32 v21, 0, v21
	v_max_f32_e32 v22, 0, v22
	v_max_f32_e32 v23, 0, v23
	v_max_f32_e32 v16, 0, v16
	v_max_f32_e32 v17, 0, v17
	v_max_f32_e32 v18, 0, v18
	v_max_f32_e32 v19, 0, v19
	v_pk_mul_f32 v[28:29], v[28:29], v[28:29]
	v_pk_mul_f32 v[30:31], v[30:31], v[30:31]
	v_pk_mul_f32 v[24:25], v[24:25], v[24:25]
	v_pk_mul_f32 v[26:27], v[26:27], v[26:27]
	v_pk_mul_f32 v[20:21], v[20:21], v[20:21]
	v_pk_mul_f32 v[22:23], v[22:23], v[22:23]
	v_pk_mul_f32 v[16:17], v[16:17], v[16:17]
	v_pk_mul_f32 v[18:19], v[18:19], v[18:19]
	v_cvt_pk_bf16_f32 v28, v28, v29
	v_cvt_pk_bf16_f32 v29, v30, v31
	v_cvt_pk_bf16_f32 v30, v24, v25
	v_cvt_pk_bf16_f32 v31, v26, v27
	global_store_dwordx4 v138, v[28:31], s[100:101]
	v_cvt_pk_bf16_f32 v20, v20, v21
	v_cvt_pk_bf16_f32 v21, v22, v23
	v_cvt_pk_bf16_f32 v22, v16, v17
	v_cvt_pk_bf16_f32 v23, v18, v19
	global_store_dwordx4 v138, v[20:23], s[100:101] offset:256
	s_add_u32 s100, s100, 0x20000
	s_addc_u32 s101, s101, 0
	v_pk_mul_f32 v[12:13], v[12:13], v[166:167] op_sel:[0,1] op_sel_hi:[1,1]
	v_pk_mul_f32 v[14:15], v[14:15], v[166:167] op_sel:[0,1] op_sel_hi:[1,1]
	v_pk_mul_f32 v[8:9], v[8:9], v[166:167] op_sel:[0,1] op_sel_hi:[1,1]
	v_pk_mul_f32 v[10:11], v[10:11], v[166:167] op_sel:[0,1] op_sel_hi:[1,1]
	v_pk_mul_f32 v[4:5], v[4:5], v[166:167] op_sel:[0,1] op_sel_hi:[1,1]
	v_pk_mul_f32 v[6:7], v[6:7], v[166:167] op_sel:[0,1] op_sel_hi:[1,1]
	v_pk_mul_f32 v[0:1], v[0:1], v[166:167] op_sel:[0,1] op_sel_hi:[1,1]
	v_pk_mul_f32 v[2:3], v[2:3], v[166:167] op_sel:[0,1] op_sel_hi:[1,1]
	v_max_f32_e32 v12, 0, v12
	v_max_f32_e32 v13, 0, v13
	v_max_f32_e32 v14, 0, v14
	v_max_f32_e32 v15, 0, v15
	v_max_f32_e32 v8, 0, v8
	v_max_f32_e32 v9, 0, v9
	v_max_f32_e32 v10, 0, v10
	v_max_f32_e32 v11, 0, v11
	v_max_f32_e32 v4, 0, v4
	v_max_f32_e32 v5, 0, v5
	v_max_f32_e32 v6, 0, v6
	v_max_f32_e32 v7, 0, v7
	v_max_f32_e32 v0, 0, v0
	v_max_f32_e32 v1, 0, v1
	v_max_f32_e32 v2, 0, v2
	v_max_f32_e32 v3, 0, v3
	v_pk_mul_f32 v[12:13], v[12:13], v[12:13]
	v_pk_mul_f32 v[14:15], v[14:15], v[14:15]
	v_pk_mul_f32 v[8:9], v[8:9], v[8:9]
	v_pk_mul_f32 v[10:11], v[10:11], v[10:11]
	v_pk_mul_f32 v[4:5], v[4:5], v[4:5]
	v_pk_mul_f32 v[6:7], v[6:7], v[6:7]
	v_pk_mul_f32 v[0:1], v[0:1], v[0:1]
	v_pk_mul_f32 v[2:3], v[2:3], v[2:3]
	v_cvt_pk_bf16_f32 v12, v12, v13
	v_cvt_pk_bf16_f32 v13, v14, v15
	v_cvt_pk_bf16_f32 v14, v8, v9
	v_cvt_pk_bf16_f32 v15, v10, v11
	global_store_dwordx4 v138, v[12:15], s[100:101]
	v_cvt_pk_bf16_f32 v4, v4, v5
	v_cvt_pk_bf16_f32 v5, v6, v7
	v_cvt_pk_bf16_f32 v6, v0, v1
	v_cvt_pk_bf16_f32 v7, v2, v3
	global_store_dwordx4 v138, v[4:7], s[100:101] offset:256
	s_andn2_b64 vcc, exec, s[4:5]
	s_cbranch_vccnz .LBB0_787
	s_andn2_b64 vcc, exec, s[0:1]
	s_cbranch_vccnz .LBB0_786
	s_barrier
	s_branch .LBB0_786
